# ple tile start: row-scale block moved after the first LDS-DMA loads (as in inproj)
# speedup vs baseline: 1.0103x; 1.0103x over previous
; DI int tid() { int t = __builtin_amdgcn_workitem_id_x(); asm volatile("" : "+v"(t)); return t; }
; #define STAGE(P, BASE, br, kt) do { const bf16_t* g_ = (BASE) + (size_t)(br) * K + (size_t)(kt) * 64; \
;         _Pragma("unroll") for (int i_ = 0; i_ < 2; ++i_) \
;             __builtin_amdgcn_global_load_lds((const unsigned*)(g_ + gofs[i_]), (lds_ptr_t)((P) + wb + i_ * 8192), 16, 0, 0); } while (0)
; #define STAGE(P, BASE, br, kt) do { const int sg_ = (kt) >> 3; const bf16_t* g_ = (sg_ == 0 ? BASE##0 : sg_ == 1 ? BASE##1 : BASE##2) + (size_t)(br) * K + (size_t)((kt) & 7) * 64; \
;         _Pragma("unroll") for (int i_ = 0; i_ < 2; ++i_) \
;             __builtin_amdgcn_global_load_lds((const unsigned*)(g_ + gofs[i_]), (lds_ptr_t)((P) + wb + i_ * 8192), 16, 0, 0); } while (0)
; DI void gemm8(f32x4 (&acc)[2][2][4][2], const bf16_t* __restrict__ Rm, const bf16_t* __restrict__ Cm, int K, char* shm) {
;     ...
;     STAGE(SB(0, 0), Cm, 0, 0); STAGE(SA(0, 0), Rm, 0, 0);
;     STAGE(SB(0, 1), Cm, 128, 0); STAGE(SA(0, 1), Rm, 128, 0);
; DI void tile_rstd(const float* __restrict__ ssq, int m0, char* lds) {
;     __syncthreads();
;     const int t = tid();
;     if (t < 256) {
;         const f32x4* p = (const f32x4*)(ssq + (size_t)(m0 + t) * 16);
;         const f32x4 a = p[0], b = p[1], c = p[2], d = p[3];
;         const float sm = ((a[0] + a[1]) + (a[2] + a[3])) + ((b[0] + b[1]) + (b[2] + b[3])) + ((c[0] + c[1]) + (c[2] + c[3])) + ((d[0] + d[1]) + (d[2] + d[3]));
;         ((float*)(lds + LDS_RS))[t] = __builtin_amdgcn_rsqf(sm * (1.f / 1024.f) + kEps);
;     }
; }
.LBB0_109:
	s_lshr_b32 s2, s58, 2
	s_and_b32 s22, s2, 64
	s_lshl_b32 s2, s58, 3
	s_and_b32 s23, s2, 56
	s_or_b32 s2, s22, s23
	s_bfe_u32 s24, s58, 0x30003
	s_or_b32 s2, s2, s24
	v_mov_b32_e32 v0, v162
	s_lshl_b32 s82, s2, 8
	v_mov_b32_e32 v0, v162
	s_ashr_i32 s2, s58, 7
	v_ashrrev_i32_e32 v3, 31, v0
	v_lshrrev_b32_e32 v3, 26, v3
	v_add_u32_e32 v3, v0, v3
	v_ashrrev_i32_e32 v10, 6, v3
	v_bfe_i32 v3, v0, 27, 1
	v_lshlrev_b32_e32 v2, 4, v0
	v_lshrrev_b32_e32 v3, 22, v3
	v_add_u32_e32 v3, v2, v3
	v_and_b32_e32 v3, 0xfffffc00, v3
	v_sub_u32_e32 v3, v2, v3
	v_lshrrev_b32_e32 v4, 4, v3
	v_bitop3_b32 v4, v4, v3, 32 bitop3:0x6c
	v_ashrrev_i32_e32 v3, 31, v3
	v_lshrrev_b32_e32 v3, 26, v3
	v_lshlrev_b32_e32 v5, 3, v10
	v_add_u32_e32 v3, v4, v3
	v_and_b32_e32 v5, 0x3ffff0, v5
	v_ashrrev_i32_e32 v11, 6, v3
	v_add_u32_e32 v3, v11, v5
	v_lshlrev_b32_e32 v5, 5, v10
	v_and_b32_e32 v12, 32, v5
	v_mul_i32_i24_e32 v5, 64, v11
	v_sub_u32_e32 v4, v4, v5
	v_ashrrev_i16_sdwa v13, v175, sext(v4) dst_sel:DWORD dst_unused:UNUSED_PAD src0_sel:DWORD src1_sel:BYTE_0
	v_lshl_or_b32 v3, v3, 10, v12
	v_add_u32_e32 v2, 0x2000, v2
	v_add_u32_sdwa v130, v3, sext(v13) dst_sel:DWORD dst_unused:UNUSED_PAD src0_sel:DWORD src1_sel:WORD_0
	v_ashrrev_i32_e32 v3, 31, v2
	v_lshrrev_b32_e32 v3, 22, v3
	v_add_u32_e32 v3, v2, v3
	v_ashrrev_i32_e32 v14, 10, v3
	v_mul_i32_i24_e32 v3, 0x400, v14
	v_sub_u32_e32 v2, v2, v3
	v_lshrrev_b32_e32 v3, 4, v2
	s_and_b32 s6, s2, -4
	s_bfe_u32 s3, s58, 0x20006
	v_bitop3_b32 v2, v3, v2, 32 bitop3:0x6c
	s_or_b32 s35, s6, s3
	v_ashrrev_i32_e32 v4, 31, v2
	s_lshl_b32 s6, s35, 8
	v_lshrrev_b32_e32 v4, 26, v4
	s_ashr_i32 s7, s6, 31
	v_lshlrev_b32_e32 v3, 3, v14
	v_add_u32_e32 v4, v2, v4
	s_lshl_b64 s[8:9], s[6:7], 11
	v_and_b32_e32 v3, 0x3ffff0, v3
	v_ashrrev_i32_e32 v16, 6, v4
	v_lshlrev_b32_e32 v5, 5, v14
	v_and_b32_e32 v4, 0xc0, v4
	s_add_u32 s8, s50, s8
	v_ashrrev_i32_e32 v15, 6, v0
	v_add_u32_e32 v3, v16, v3
	v_and_b32_e32 v17, 32, v5
	v_sub_u32_e32 v2, v2, v4
	s_addc_u32 s9, s51, s9
	s_lshl_b32 s16, s82, 11
	v_ashrrev_i16_sdwa v18, v175, sext(v2) dst_sel:DWORD dst_unused:UNUSED_PAD src0_sel:DWORD src1_sel:BYTE_0
	v_lshl_or_b32 v2, v3, 10, v17
	v_lshlrev_b32_e32 v146, 10, v15
	s_add_u32 s16, s10, s16
	v_add_u32_sdwa v132, v2, sext(v18) dst_sel:DWORD dst_unused:UNUSED_PAD src0_sel:DWORD src1_sel:WORD_0
	v_add_u32_e32 v147, 0x10000, v146
	v_ashrrev_i32_e32 v131, 31, v130
	s_addc_u32 s17, s11, 0
	v_lshlrev_b64 v[20:21], 1, v[130:131]
	v_readfirstlane_b32 s20, v147
	v_ashrrev_i32_e32 v133, 31, v132
	v_add_u32_e32 v148, 0x12000, v146
	v_lshl_add_u64 v[2:3], s[16:17], 0, v[20:21]
	s_mov_b32 m0, s20
	v_lshlrev_b64 v[22:23], 1, v[132:133]
	v_readfirstlane_b32 s20, v148
	global_load_lds_dwordx4 v[2:3], off
	v_lshl_add_u64 v[6:7], s[16:17], 0, v[22:23]
	s_mov_b32 m0, s20
	v_readfirstlane_b32 s20, v146
	v_add_u32_e32 v150, 0x2000, v146
	global_load_lds_dwordx4 v[6:7], off
	v_lshl_add_u64 v[8:9], s[8:9], 0, v[20:21]
	s_mov_b32 m0, s20
	v_readfirstlane_b32 s20, v150
	global_load_lds_dwordx4 v[8:9], off
	s_mov_b32 m0, s20
	s_add_u32 s20, s16, 0x40000
	v_add_u32_e32 v151, 0x14000, v146
	v_lshl_add_u64 v[4:5], s[8:9], 0, v[22:23]
	s_addc_u32 s21, s17, 0
	v_readfirstlane_b32 s25, v151
	global_load_lds_dwordx4 v[4:5], off
	v_lshl_add_u64 v[24:25], s[20:21], 0, v[20:21]
	s_mov_b32 m0, s25
	v_add_u32_e32 v152, 0x16000, v146
	global_load_lds_dwordx4 v[24:25], off
	v_lshl_add_u64 v[24:25], s[20:21], 0, v[22:23]
	v_readfirstlane_b32 s20, v152
	s_mov_b32 m0, s20
	s_add_u32 s20, s8, 0x40000
	v_add_u32_e32 v153, 0x4000, v146
	s_addc_u32 s21, s9, 0
	v_readfirstlane_b32 s25, v153
	global_load_lds_dwordx4 v[24:25], off
	v_lshl_add_u64 v[20:21], s[20:21], 0, v[20:21]
	s_mov_b32 m0, s25
	v_add_u32_e32 v154, 0x6000, v146
	global_load_lds_dwordx4 v[20:21], off
	v_lshl_add_u64 v[20:21], s[20:21], 0, v[22:23]
	v_readfirstlane_b32 s20, v154
	s_mov_b32 m0, s20
	v_ashrrev_i32_e32 v19, 8, v0
	global_load_lds_dwordx4 v[20:21], off
	s_waitcnt lgkmcnt(0)
	s_barrier
	v_cmp_gt_i32_e32 vcc, s96, v162
	s_and_saveexec_b64 s[98:99], vcc
	s_cbranch_execz .Lrs_skipP
	v_add_u32_e32 v186, s82, v162
	v_ashrrev_i32_e32 v187, 31, v186
	v_readlane_b32 s0, v253, 32
	v_lshlrev_b64 v[186:187], 6, v[186:187]
	v_readlane_b32 s1, v253, 33
	v_lshl_add_u32 v184, v162, 2, v177
	s_nop 0
	v_lshl_add_u64 v[198:199], s[0:1], 0, v[186:187]
	global_load_dwordx4 v[186:189], v[198:199], off offset:48
	global_load_dwordx4 v[190:193], v[198:199], off offset:32
	global_load_dwordx4 v[194:197], v[198:199], off offset:16
	s_nop 0
	global_load_dwordx4 v[198:201], v[198:199], off
	s_waitcnt vmcnt(2)
	v_add_f32_e32 v190, v190, v191
	v_add_f32_e32 v192, v192, v193
	s_waitcnt vmcnt(0)
	v_mov_b32_e32 v202, v199
	v_mov_b32_e32 v203, v200
	v_mov_b32_e32 v199, v201
	v_mov_b32_e32 v200, v195
	v_mov_b32_e32 v201, v196
	v_mov_b32_e32 v195, v197
	v_pk_add_f32 v[198:199], v[202:203], v[198:199]
	v_pk_add_f32 v[194:195], v[200:201], v[194:195]
	v_pk_add_f32 v[198:199], v[198:199], v[198:199] op_sel:[0,1] op_sel_hi:[1,0]
	v_pk_add_f32 v[194:195], v[194:195], v[194:195] op_sel:[0,1] op_sel_hi:[1,0]
	v_mov_b32_e32 v199, v186
	v_mov_b32_e32 v195, v187
	v_mov_b32_e32 v191, v188
	v_mov_b32_e32 v193, v189
	v_pk_add_f32 v[186:187], v[198:199], v[194:195]
	v_pk_add_f32 v[188:189], v[190:191], v[192:193]
	s_nop 0
	v_pk_add_f32 v[186:187], v[186:187], v[188:189]
	s_nop 0
	v_add_f32_e32 v186, v186, v187
	v_fmamk_f32 v186, v186, 0x3a800000, v163
	v_rsq_f32_e32 v186, v186
	ds_write_b32 v184, v186
.Lrs_skipP:
	s_or_b64 exec, exec, s[98:99]
	v_cmp_eq_u32_e32 vcc, 1, v19
	s_and_saveexec_b64 s[20:21], vcc
	s_cbranch_execz .LBB0_113
	s_barrier
